# SwiGLU epilogue: store data and address operands moved from accumulator registers to dead fragment registers (tests whether next-unit accumulator writes wait on pending store operand reads); on zl2 st
# baseline (speedup 1.0000x reference)
.LBB0_1063:
	v_mul_f32_e32 v144, 0xbfb8aa3b, v126
	v_exp_f32_e32 v144, v144
	v_lshl_or_b32 v142, s25, 7, v139
	v_lshl_add_u32 v141, s24, 8, v137
	v_ashrrev_i32_e32 v143, 31, v142
	v_add_f32_e32 v144, 1.0, v144
	v_rcp_f32_e32 v144, v144
	s_andn2_b64 vcc, exec, s[4:5]
	v_mul_f32_e32 v126, v126, v144
	v_mul_f32_e32 v122, v126, v122
	v_mul_f32_e32 v126, 0xbfb8aa3b, v127
	v_exp_f32_e32 v126, v126
	s_nop 0
	v_add_f32_e32 v126, 1.0, v126
	v_rcp_f32_e32 v126, v126
	s_nop 0
	v_mul_f32_e32 v126, v127, v126
	v_mul_f32_e32 v123, v126, v123
	v_mul_f32_e32 v126, 0xbfb8aa3b, v128
	v_exp_f32_e32 v126, v126
	s_nop 0
	v_add_f32_e32 v126, 1.0, v126
	v_rcp_f32_e32 v126, v126
	s_nop 0
	v_mul_f32_e32 v126, v128, v126
	v_mul_f32_e32 v124, v126, v124
	v_mul_f32_e32 v126, 0xbfb8aa3b, v129
	v_exp_f32_e32 v126, v126
	s_nop 0
	v_add_f32_e32 v126, 1.0, v126
	v_rcp_f32_e32 v126, v126
	s_nop 0
	v_mul_f32_e32 v126, v129, v126
	v_mul_f32_e32 v125, v126, v125
	v_mul_f32_e32 v126, 0xbfb8aa3b, v118
	v_exp_f32_e32 v126, v126
	s_nop 0
	v_add_f32_e32 v126, 1.0, v126
	v_rcp_f32_e32 v126, v126
	s_nop 0
	v_mul_f32_e32 v118, v118, v126
	v_mul_f32_e32 v114, v118, v114
	v_mul_f32_e32 v118, 0xbfb8aa3b, v119
	v_exp_f32_e32 v118, v118
	s_nop 0
	v_add_f32_e32 v118, 1.0, v118
	v_rcp_f32_e32 v118, v118
	s_nop 0
	v_mul_f32_e32 v118, v119, v118
	v_mul_f32_e32 v115, v118, v115
	v_mul_f32_e32 v118, 0xbfb8aa3b, v120
	v_exp_f32_e32 v118, v118
	s_nop 0
	v_add_f32_e32 v118, 1.0, v118
	v_rcp_f32_e32 v118, v118
	s_nop 0
	v_mul_f32_e32 v118, v120, v118
	v_mul_f32_e32 v116, v118, v116
	v_mul_f32_e32 v118, 0xbfb8aa3b, v121
	v_exp_f32_e32 v118, v118
	s_nop 0
	v_add_f32_e32 v118, 1.0, v118
	v_rcp_f32_e32 v118, v118
	s_nop 0
	v_mul_f32_e32 v118, v121, v118
	v_mul_f32_e32 v117, v118, v117
	v_cvt_pk_bf16_f32 v150, v122, v123
	v_cvt_pk_bf16_f32 v151, v124, v125
	v_cvt_pk_bf16_f32 v152, v114, v115
	v_mov_b64_e32 v[114:115], s[10:11]
	v_cvt_pk_bf16_f32 v153, v116, v117
	v_mad_i64_i32 v[154:155], s[24:25], v141, s53, v[114:115]
	v_lshlrev_b64 v[116:117], 1, v[142:143]
	v_lshl_add_u64 v[154:155], v[154:155], 0, v[116:117]
	global_store_dwordx4 v[154:155], v[150:153], off
	s_nop 1
	v_mul_f32_e32 v118, 0xbfb8aa3b, v110
	v_exp_f32_e32 v118, v118
	s_nop 0
	v_add_f32_e32 v118, 1.0, v118
	v_rcp_f32_e32 v118, v118
	s_nop 0
	v_mul_f32_e32 v110, v110, v118
	v_mul_f32_e32 v106, v110, v106
	v_mul_f32_e32 v110, 0xbfb8aa3b, v111
	v_exp_f32_e32 v110, v110
	s_nop 0
	v_add_f32_e32 v110, 1.0, v110
	v_rcp_f32_e32 v110, v110
	s_nop 0
	v_mul_f32_e32 v110, v111, v110
	v_mul_f32_e32 v107, v110, v107
	v_mul_f32_e32 v110, 0xbfb8aa3b, v112
	v_exp_f32_e32 v110, v110
	s_nop 0
	v_add_f32_e32 v110, 1.0, v110
	v_rcp_f32_e32 v110, v110
	s_nop 0
	v_mul_f32_e32 v110, v112, v110
	v_mul_f32_e32 v108, v110, v108
	v_mul_f32_e32 v110, 0xbfb8aa3b, v113
	v_exp_f32_e32 v110, v110
	s_nop 0
	v_add_f32_e32 v110, 1.0, v110
	v_rcp_f32_e32 v110, v110
	s_nop 0
	v_mul_f32_e32 v110, v113, v110
	v_mul_f32_e32 v109, v110, v109
	v_mul_f32_e32 v110, 0xbfb8aa3b, v102
	v_exp_f32_e32 v110, v110
	s_nop 0
	v_add_f32_e32 v110, 1.0, v110
	v_rcp_f32_e32 v110, v110
	s_nop 0
	v_mul_f32_e32 v102, v102, v110
	v_mul_f32_e32 v102, v102, v98
	v_mul_f32_e32 v98, 0xbfb8aa3b, v103
	v_exp_f32_e32 v98, v98
	s_nop 0
	v_add_f32_e32 v98, 1.0, v98
	v_rcp_f32_e32 v98, v98
	s_nop 0
	v_mul_f32_e32 v98, v103, v98
	v_mul_f32_e32 v103, v98, v99
	v_mul_f32_e32 v98, 0xbfb8aa3b, v104
	v_exp_f32_e32 v98, v98
	s_nop 0
	v_add_f32_e32 v98, 1.0, v98
	v_rcp_f32_e32 v98, v98
	s_nop 0
	v_mul_f32_e32 v98, v104, v98
	v_mul_f32_e32 v104, v98, v100
	v_mul_f32_e32 v98, 0xbfb8aa3b, v105
	v_exp_f32_e32 v98, v98
	s_nop 0
	v_add_f32_e32 v98, 1.0, v98
	v_rcp_f32_e32 v98, v98
	s_nop 0
	v_mul_f32_e32 v98, v105, v98
	v_or_b32_e32 v105, 16, v141
	v_mul_f32_e32 v101, v98, v101
	v_cvt_pk_bf16_f32 v156, v106, v107
	v_cvt_pk_bf16_f32 v157, v108, v109
	v_cvt_pk_bf16_f32 v158, v102, v103
	v_mad_i64_i32 v[160:161], s[24:25], v105, s53, v[114:115]
	v_lshl_add_u64 v[160:161], v[160:161], 0, v[116:117]
	v_cvt_pk_bf16_f32 v159, v104, v101
	global_store_dwordx4 v[160:161], v[156:159], off
	s_nop 1
	v_mul_f32_e32 v98, 0xbfb8aa3b, v94
	v_exp_f32_e32 v98, v98
	s_nop 0
	v_add_f32_e32 v98, 1.0, v98
	v_rcp_f32_e32 v98, v98
	s_nop 0
	v_mul_f32_e32 v94, v94, v98
	v_mul_f32_e32 v90, v94, v90
	v_mul_f32_e32 v94, 0xbfb8aa3b, v95
	v_exp_f32_e32 v94, v94
	s_nop 0
	v_add_f32_e32 v94, 1.0, v94
	v_rcp_f32_e32 v94, v94
	s_nop 0
	v_mul_f32_e32 v94, v95, v94
	v_mul_f32_e32 v91, v94, v91
	v_mul_f32_e32 v94, 0xbfb8aa3b, v96
	v_exp_f32_e32 v94, v94
	s_nop 0
	v_add_f32_e32 v94, 1.0, v94
	v_rcp_f32_e32 v94, v94
	s_nop 0
	v_mul_f32_e32 v94, v96, v94
	v_mul_f32_e32 v92, v94, v92
	v_mul_f32_e32 v94, 0xbfb8aa3b, v97
	v_exp_f32_e32 v94, v94
	s_nop 0
	v_add_f32_e32 v94, 1.0, v94
	v_rcp_f32_e32 v94, v94
	s_nop 0
	v_mul_f32_e32 v94, v97, v94
	v_mul_f32_e32 v93, v94, v93
	v_mul_f32_e32 v94, 0xbfb8aa3b, v86
	v_exp_f32_e32 v94, v94
	s_nop 0
	v_add_f32_e32 v94, 1.0, v94
	v_rcp_f32_e32 v94, v94
	s_nop 0
	v_mul_f32_e32 v86, v86, v94
	v_mul_f32_e32 v86, v86, v82
	v_mul_f32_e32 v82, 0xbfb8aa3b, v87
	v_exp_f32_e32 v82, v82
	s_nop 0
	v_add_f32_e32 v82, 1.0, v82
	v_rcp_f32_e32 v82, v82
	s_nop 0
	v_mul_f32_e32 v82, v87, v82
	v_mul_f32_e32 v87, v82, v83
	v_mul_f32_e32 v82, 0xbfb8aa3b, v88
	v_exp_f32_e32 v82, v82
	s_nop 0
	v_add_f32_e32 v82, 1.0, v82
	v_rcp_f32_e32 v82, v82
	s_nop 0
	v_mul_f32_e32 v82, v88, v82
	v_mul_f32_e32 v88, v82, v84
	v_mul_f32_e32 v82, 0xbfb8aa3b, v89
	v_exp_f32_e32 v82, v82
	s_nop 0
	v_add_f32_e32 v82, 1.0, v82
	v_rcp_f32_e32 v82, v82
	s_nop 0
	v_mul_f32_e32 v82, v89, v82
	v_or_b32_e32 v89, 32, v141
	v_mul_f32_e32 v85, v82, v85
	v_cvt_pk_bf16_f32 v162, v90, v91
	v_cvt_pk_bf16_f32 v163, v92, v93
	v_cvt_pk_bf16_f32 v164, v86, v87
	v_mad_i64_i32 v[166:167], s[24:25], v89, s53, v[114:115]
	v_lshl_add_u64 v[166:167], v[166:167], 0, v[116:117]
	v_cvt_pk_bf16_f32 v165, v88, v85
	global_store_dwordx4 v[166:167], v[162:165], off
	s_nop 1
	v_mul_f32_e32 v82, 0xbfb8aa3b, v78
	v_exp_f32_e32 v82, v82
	s_nop 0
	v_add_f32_e32 v82, 1.0, v82
	v_rcp_f32_e32 v82, v82
	s_nop 0
	v_mul_f32_e32 v78, v78, v82
	v_mul_f32_e32 v74, v78, v74
	v_mul_f32_e32 v78, 0xbfb8aa3b, v79
	v_exp_f32_e32 v78, v78
	s_nop 0
	v_add_f32_e32 v78, 1.0, v78
	v_rcp_f32_e32 v78, v78
	s_nop 0
	v_mul_f32_e32 v78, v79, v78
	v_mul_f32_e32 v75, v78, v75
	v_mul_f32_e32 v78, 0xbfb8aa3b, v80
	v_exp_f32_e32 v78, v78
	s_nop 0
	v_add_f32_e32 v78, 1.0, v78
	v_rcp_f32_e32 v78, v78
	s_nop 0
	v_mul_f32_e32 v78, v80, v78
	v_mul_f32_e32 v76, v78, v76
	v_mul_f32_e32 v78, 0xbfb8aa3b, v81
	v_exp_f32_e32 v78, v78
	s_nop 0
	v_add_f32_e32 v78, 1.0, v78
	v_rcp_f32_e32 v78, v78
	s_nop 0
	v_mul_f32_e32 v78, v81, v78
	v_mul_f32_e32 v77, v78, v77
	v_mul_f32_e32 v78, 0xbfb8aa3b, v70
	v_exp_f32_e32 v78, v78
	s_nop 0
	v_add_f32_e32 v78, 1.0, v78
	v_rcp_f32_e32 v78, v78
	s_nop 0
	v_mul_f32_e32 v70, v70, v78
	v_mul_f32_e32 v70, v70, v66
	v_mul_f32_e32 v66, 0xbfb8aa3b, v71
	v_exp_f32_e32 v66, v66
	s_nop 0
	v_add_f32_e32 v66, 1.0, v66
	v_rcp_f32_e32 v66, v66
	s_nop 0
	v_mul_f32_e32 v66, v71, v66
	v_mul_f32_e32 v71, v66, v67
	v_mul_f32_e32 v66, 0xbfb8aa3b, v72
	v_exp_f32_e32 v66, v66
	s_nop 0
	v_add_f32_e32 v66, 1.0, v66
	v_rcp_f32_e32 v66, v66
	s_nop 0
	v_mul_f32_e32 v66, v72, v66
	v_mul_f32_e32 v72, v66, v68
	v_mul_f32_e32 v66, 0xbfb8aa3b, v73
	v_exp_f32_e32 v66, v66
	s_nop 0
	v_add_f32_e32 v66, 1.0, v66
	v_rcp_f32_e32 v66, v66
	s_nop 0
	v_mul_f32_e32 v66, v73, v66
	v_or_b32_e32 v73, 48, v141
	v_mul_f32_e32 v69, v66, v69
	v_cvt_pk_bf16_f32 v168, v74, v75
	v_cvt_pk_bf16_f32 v169, v76, v77
	v_cvt_pk_bf16_f32 v170, v70, v71
	v_mad_i64_i32 v[172:173], s[24:25], v73, s53, v[114:115]
	v_lshl_add_u64 v[172:173], v[172:173], 0, v[116:117]
	v_cvt_pk_bf16_f32 v171, v72, v69
	global_store_dwordx4 v[172:173], v[168:171], off
	s_nop 1
	v_mul_f32_e32 v67, 0xbfb8aa3b, v62
	v_exp_f32_e32 v67, v67
	v_add_u32_e32 v66, 0x80, v141
	v_add_f32_e32 v67, 1.0, v67
	v_rcp_f32_e32 v67, v67
	s_nop 0
	v_mul_f32_e32 v62, v62, v67
	v_mul_f32_e32 v58, v62, v58
	v_mul_f32_e32 v62, 0xbfb8aa3b, v63
	v_exp_f32_e32 v62, v62
	s_nop 0
	v_add_f32_e32 v62, 1.0, v62
	v_rcp_f32_e32 v62, v62
	s_nop 0
	v_mul_f32_e32 v62, v63, v62
	v_mul_f32_e32 v59, v62, v59
	v_mul_f32_e32 v62, 0xbfb8aa3b, v64
	v_exp_f32_e32 v62, v62
	s_nop 0
	v_add_f32_e32 v62, 1.0, v62
	v_rcp_f32_e32 v62, v62
	s_nop 0
	v_mul_f32_e32 v62, v64, v62
	v_mul_f32_e32 v60, v62, v60
	v_mul_f32_e32 v62, 0xbfb8aa3b, v65
	v_exp_f32_e32 v62, v62
	s_nop 0
	v_add_f32_e32 v62, 1.0, v62
	v_rcp_f32_e32 v62, v62
	s_nop 0
	v_mul_f32_e32 v62, v65, v62
	v_mul_f32_e32 v61, v62, v61
	v_mul_f32_e32 v62, 0xbfb8aa3b, v54
	v_exp_f32_e32 v62, v62
	s_nop 0
	v_add_f32_e32 v62, 1.0, v62
	v_rcp_f32_e32 v62, v62
	s_nop 0
	v_mul_f32_e32 v54, v54, v62
	v_mul_f32_e32 v54, v54, v50
	v_mul_f32_e32 v50, 0xbfb8aa3b, v55
	v_exp_f32_e32 v50, v50
	s_nop 0
	v_add_f32_e32 v50, 1.0, v50
	v_rcp_f32_e32 v50, v50
	s_nop 0
	v_mul_f32_e32 v50, v55, v50
	v_mul_f32_e32 v55, v50, v51
	v_mul_f32_e32 v50, 0xbfb8aa3b, v56
	v_exp_f32_e32 v50, v50
	s_nop 0
	v_add_f32_e32 v50, 1.0, v50
	v_rcp_f32_e32 v50, v50
	s_nop 0
	v_mul_f32_e32 v50, v56, v50
	v_mul_f32_e32 v56, v50, v52
	v_mul_f32_e32 v50, 0xbfb8aa3b, v57
	v_exp_f32_e32 v50, v50
	s_nop 0
	v_add_f32_e32 v50, 1.0, v50
	v_rcp_f32_e32 v50, v50
	s_nop 0
	v_mul_f32_e32 v50, v57, v50
	v_mul_f32_e32 v53, v50, v53
	v_cvt_pk_bf16_f32 v174, v58, v59
	v_cvt_pk_bf16_f32 v175, v60, v61
	v_cvt_pk_bf16_f32 v176, v54, v55
	v_mad_i64_i32 v[178:179], s[24:25], v66, s53, v[114:115]
	v_lshl_add_u64 v[178:179], v[178:179], 0, v[116:117]
	v_cvt_pk_bf16_f32 v177, v56, v53
	global_store_dwordx4 v[178:179], v[174:177], off
	s_nop 1
	v_mul_f32_e32 v50, 0xbfb8aa3b, v46
	v_exp_f32_e32 v50, v50
	s_nop 0
	v_add_f32_e32 v50, 1.0, v50
	v_rcp_f32_e32 v50, v50
	s_nop 0
	v_mul_f32_e32 v46, v46, v50
	v_mul_f32_e32 v42, v46, v42
	v_mul_f32_e32 v46, 0xbfb8aa3b, v47
	v_exp_f32_e32 v46, v46
	s_nop 0
	v_add_f32_e32 v46, 1.0, v46
	v_rcp_f32_e32 v46, v46
	s_nop 0
	v_mul_f32_e32 v46, v47, v46
	v_mul_f32_e32 v43, v46, v43
	v_mul_f32_e32 v46, 0xbfb8aa3b, v48
	v_exp_f32_e32 v46, v46
	s_nop 0
	v_add_f32_e32 v46, 1.0, v46
	v_rcp_f32_e32 v46, v46
	s_nop 0
	v_mul_f32_e32 v46, v48, v46
	v_mul_f32_e32 v44, v46, v44
	v_mul_f32_e32 v46, 0xbfb8aa3b, v49
	v_exp_f32_e32 v46, v46
	s_nop 0
	v_add_f32_e32 v46, 1.0, v46
	v_rcp_f32_e32 v46, v46
	s_nop 0
	v_mul_f32_e32 v46, v49, v46
	v_mul_f32_e32 v45, v46, v45
	v_mul_f32_e32 v46, 0xbfb8aa3b, v38
	v_exp_f32_e32 v46, v46
	s_nop 0
	v_add_f32_e32 v46, 1.0, v46
	v_rcp_f32_e32 v46, v46
	s_nop 0
	v_mul_f32_e32 v38, v38, v46
	v_mul_f32_e32 v38, v38, v34
	v_mul_f32_e32 v34, 0xbfb8aa3b, v39
	v_exp_f32_e32 v34, v34
	s_nop 0
	v_add_f32_e32 v34, 1.0, v34
	v_rcp_f32_e32 v34, v34
	s_nop 0
	v_mul_f32_e32 v34, v39, v34
	v_mul_f32_e32 v39, v34, v35
	v_mul_f32_e32 v34, 0xbfb8aa3b, v40
	v_exp_f32_e32 v34, v34
	s_nop 0
	v_add_f32_e32 v34, 1.0, v34
	v_rcp_f32_e32 v34, v34
	s_nop 0
	v_mul_f32_e32 v34, v40, v34
	v_mul_f32_e32 v40, v34, v36
	v_mul_f32_e32 v34, 0xbfb8aa3b, v41
	v_exp_f32_e32 v34, v34
	s_nop 0
	v_add_f32_e32 v34, 1.0, v34
	v_rcp_f32_e32 v34, v34
	s_nop 0
	v_mul_f32_e32 v34, v41, v34
	v_add_u32_e32 v41, 0x90, v141
	v_mul_f32_e32 v37, v34, v37
	v_cvt_pk_bf16_f32 v180, v42, v43
	v_cvt_pk_bf16_f32 v181, v44, v45
	v_cvt_pk_bf16_f32 v182, v38, v39
	v_mad_i64_i32 v[184:185], s[24:25], v41, s53, v[114:115]
	v_lshl_add_u64 v[184:185], v[184:185], 0, v[116:117]
	v_cvt_pk_bf16_f32 v183, v40, v37
	global_store_dwordx4 v[184:185], v[180:183], off
	s_nop 1
	v_mul_f32_e32 v34, 0xbfb8aa3b, v30
	v_exp_f32_e32 v34, v34
	s_nop 0
	v_add_f32_e32 v34, 1.0, v34
	v_rcp_f32_e32 v34, v34
	s_nop 0
	v_mul_f32_e32 v30, v30, v34
	v_mul_f32_e32 v26, v30, v26
	v_mul_f32_e32 v30, 0xbfb8aa3b, v31
	v_exp_f32_e32 v30, v30
	s_nop 0
	v_add_f32_e32 v30, 1.0, v30
	v_rcp_f32_e32 v30, v30
	s_nop 0
	v_mul_f32_e32 v30, v31, v30
	v_mul_f32_e32 v27, v30, v27
	v_mul_f32_e32 v30, 0xbfb8aa3b, v32
	v_exp_f32_e32 v30, v30
	s_nop 0
	v_add_f32_e32 v30, 1.0, v30
	v_rcp_f32_e32 v30, v30
	s_nop 0
	v_mul_f32_e32 v30, v32, v30
	v_mul_f32_e32 v28, v30, v28
	v_mul_f32_e32 v30, 0xbfb8aa3b, v33
	v_exp_f32_e32 v30, v30
	s_nop 0
	v_add_f32_e32 v30, 1.0, v30
	v_rcp_f32_e32 v30, v30
	s_nop 0
	v_mul_f32_e32 v30, v33, v30
	v_mul_f32_e32 v29, v30, v29
	v_mul_f32_e32 v30, 0xbfb8aa3b, v22
	v_exp_f32_e32 v30, v30
	s_nop 0
	v_add_f32_e32 v30, 1.0, v30
	v_rcp_f32_e32 v30, v30
	s_nop 0
	v_mul_f32_e32 v22, v22, v30
	v_mul_f32_e32 v22, v22, v18
	v_mul_f32_e32 v18, 0xbfb8aa3b, v23
	v_exp_f32_e32 v18, v18
	s_nop 0
	v_add_f32_e32 v18, 1.0, v18
	v_rcp_f32_e32 v18, v18
	s_nop 0
	v_mul_f32_e32 v18, v23, v18
	v_mul_f32_e32 v23, v18, v19
	v_mul_f32_e32 v18, 0xbfb8aa3b, v24
	v_exp_f32_e32 v18, v18
	s_nop 0
	v_add_f32_e32 v18, 1.0, v18
	v_rcp_f32_e32 v18, v18
	s_nop 0
	v_mul_f32_e32 v18, v24, v18
	v_mul_f32_e32 v24, v18, v20
	v_mul_f32_e32 v18, 0xbfb8aa3b, v25
	v_exp_f32_e32 v18, v18
	s_nop 0
	v_add_f32_e32 v18, 1.0, v18
	v_rcp_f32_e32 v18, v18
	s_nop 0
	v_mul_f32_e32 v18, v25, v18
	v_add_u32_e32 v25, 0xa0, v141
	v_mul_f32_e32 v21, v18, v21
	v_cvt_pk_bf16_f32 v186, v26, v27
	v_cvt_pk_bf16_f32 v187, v28, v29
	v_cvt_pk_bf16_f32 v188, v22, v23
	v_mad_i64_i32 v[190:191], s[24:25], v25, s53, v[114:115]
	v_lshl_add_u64 v[190:191], v[190:191], 0, v[116:117]
	v_cvt_pk_bf16_f32 v189, v24, v21
	global_store_dwordx4 v[190:191], v[186:189], off
	s_nop 1
	v_mul_f32_e32 v18, 0xbfb8aa3b, v14
	v_exp_f32_e32 v18, v18
	s_nop 0
	v_add_f32_e32 v18, 1.0, v18
	v_rcp_f32_e32 v18, v18
	s_nop 0
	v_mul_f32_e32 v14, v14, v18
	v_mul_f32_e32 v10, v14, v10
	v_mul_f32_e32 v14, 0xbfb8aa3b, v15
	v_exp_f32_e32 v14, v14
	s_nop 0
	v_add_f32_e32 v14, 1.0, v14
	v_rcp_f32_e32 v14, v14
	s_nop 0
	v_mul_f32_e32 v14, v15, v14
	v_mul_f32_e32 v11, v14, v11
	v_mul_f32_e32 v14, 0xbfb8aa3b, v16
	v_exp_f32_e32 v14, v14
	s_nop 0
	v_add_f32_e32 v14, 1.0, v14
	v_rcp_f32_e32 v14, v14
	s_nop 0
	v_mul_f32_e32 v14, v16, v14
	v_mul_f32_e32 v12, v14, v12
	v_mul_f32_e32 v14, 0xbfb8aa3b, v17
	v_exp_f32_e32 v14, v14
	s_nop 0
	v_add_f32_e32 v14, 1.0, v14
	v_rcp_f32_e32 v14, v14
	s_nop 0
	v_mul_f32_e32 v14, v17, v14
	v_mul_f32_e32 v13, v14, v13
	v_mul_f32_e32 v14, 0xbfb8aa3b, v6
	v_exp_f32_e32 v14, v14
	s_nop 0
	v_add_f32_e32 v14, 1.0, v14
	v_rcp_f32_e32 v14, v14
	s_nop 0
	v_mul_f32_e32 v6, v6, v14
	v_mul_f32_e32 v6, v6, v2
	v_mul_f32_e32 v2, 0xbfb8aa3b, v7
	v_exp_f32_e32 v2, v2
	s_nop 0
	v_add_f32_e32 v2, 1.0, v2
	v_rcp_f32_e32 v2, v2
	s_nop 0
	v_mul_f32_e32 v2, v7, v2
	v_mul_f32_e32 v7, v2, v3
	v_mul_f32_e32 v2, 0xbfb8aa3b, v8
	v_exp_f32_e32 v2, v2
	s_nop 0
	v_add_f32_e32 v2, 1.0, v2
	v_rcp_f32_e32 v2, v2
	s_nop 0
	v_mul_f32_e32 v2, v8, v2
	v_mul_f32_e32 v8, v2, v4
	v_mul_f32_e32 v2, 0xbfb8aa3b, v9
	v_exp_f32_e32 v2, v2
	s_nop 0
	v_add_f32_e32 v2, 1.0, v2
	v_rcp_f32_e32 v2, v2
	s_nop 0
	v_mul_f32_e32 v2, v9, v2
	v_add_u32_e32 v9, 0xb0, v141
	v_mul_f32_e32 v5, v2, v5
	v_cvt_pk_bf16_f32 v192, v10, v11
	v_cvt_pk_bf16_f32 v193, v12, v13
	v_cvt_pk_bf16_f32 v194, v6, v7
	v_mad_i64_i32 v[196:197], s[24:25], v9, s53, v[114:115]
	v_lshl_add_u64 v[196:197], v[196:197], 0, v[116:117]
	s_mov_b64 s[24:25], -1
	v_cvt_pk_bf16_f32 v195, v8, v5
	global_store_dwordx4 v[196:197], v[192:195], off
	s_cbranch_vccnz .LBB0_1056
	s_andn2_b64 vcc, exec, s[8:9]
	s_cbranch_vccnz .LBB0_1055
	s_barrier
	s_branch .LBB0_1055
